# v24 + redundant canonicalizing v_max removed in attention row-max trees (inputs never sNaN)
# baseline (speedup 1.0000x reference)
; DI unsigned pk_bf16(float a, float b) { f32x2 v = {a, b}; bf2_t r = __builtin_convertvector(v, bf2_t); return __builtin_bit_cast(unsigned, r); }
; DI float xhalf_max(float v) { const auto r = __builtin_amdgcn_permlane32_swap(__float_as_uint(v), __float_as_uint(v), false, false); return fmaxf(__uint_as_float(r[0]), __uint_as_float(r[1])); }
;     ...
;             float mx = s[0][0];
; #pragma unroll
;             for (int i = 1; i < 16; ++i) mx = fmaxf(mx, s[0][i]);
; #pragma unroll
;             for (int i = 0; i < 16; ++i) mx = fmaxf(mx, s[1][i]);
;             mx = xhalf_max(mx);
;             const float mabs = mi + mx;
;             const bool up = mabs > m + 8.0f;
;             const float mn = up ? __uint_as_float(pk_bf16(mabs, 0.f) << 16) : m;
;             const float shift = mn - mi;
;             if (__ballot(shift != 0.f) != 0) {
;                 if (__ballot(up) != 0) {
;                     const float alpha = __builtin_amdgcn_exp2f(m - mn);
;                     l *= alpha;
; #pragma unroll
;                     for (int db = 0; db < DVB; ++db)
; #pragma unroll
;                         for (int i = 0; i < 16; ++i) o[db][i] *= alpha;
;                     m = mn;
.LBB0_1268:
	s_or_b64 exec, exec, s[8:9]
	v_max_f32_e32 v2, v131, v131
	v_max_f32_e32 v4, v130, v130
	v_max_f32_e32 v2, v4, v2
	v_max3_f32 v2, v2, v132, v133
	v_max3_f32 v2, v2, v134, v135
	v_max3_f32 v2, v2, v136, v137
	v_max3_f32 v2, v2, v138, v139
	v_max3_f32 v2, v2, v140, v141
	v_max3_f32 v2, v2, v142, v143
	v_max3_f32 v2, v2, v144, v145
	v_max3_f32 v2, v2, v114, v115
	v_max3_f32 v2, v2, v116, v117
	v_max3_f32 v2, v2, v118, v119
	v_max3_f32 v2, v2, v120, v121
	v_max3_f32 v2, v2, v122, v123
	v_max3_f32 v2, v2, v124, v125
	v_max3_f32 v2, v2, v126, v127
	v_max3_f32 v2, v2, v128, v129
	v_mov_b32_e32 v4, v2
	s_nop 1
	v_permlane32_swap_b32_e32 v2, v4
	v_max_f32_e32 v198, v2, v4
	v_pk_add_f32 v[4:5], v[206:207], v[198:199]
	s_nop 0
	v_cvt_pk_bf16_f32 v2, v4, 0
	v_lshlrev_b32_e32 v2, 16, v2
	v_cmp_gt_f32_e64 s[8:9], v4, v5
	s_nop 1
	v_cndmask_b32_e64 v4, v207, v2, s[8:9]
	v_sub_f32_e32 v2, v4, v206
	v_cmp_neq_f32_e32 vcc, 0, v2
	s_cbranch_vccz .LBB0_1273
	v_cndmask_b32_e64 v5, 0, 1, s[8:9]
	v_cmp_ne_u32_e32 vcc, 0, v5
	s_cbranch_vccz .LBB0_1271
	v_sub_f32_e32 v5, v207, v4
	v_exp_f32_e32 v8, v5
	s_nop 0
	v_mul_f32_e32 v6, v6, v8
	v_pk_mul_f32 v[112:113], v[112:113], v[8:9] op_sel_hi:[1,0]
	v_pk_mul_f32 v[110:111], v[110:111], v[8:9] op_sel_hi:[1,0]
	v_pk_mul_f32 v[108:109], v[108:109], v[8:9] op_sel_hi:[1,0]
	v_pk_mul_f32 v[106:107], v[106:107], v[8:9] op_sel_hi:[1,0]
	v_pk_mul_f32 v[104:105], v[104:105], v[8:9] op_sel_hi:[1,0]
	v_pk_mul_f32 v[102:103], v[102:103], v[8:9] op_sel_hi:[1,0]
	v_pk_mul_f32 v[100:101], v[100:101], v[8:9] op_sel_hi:[1,0]
	v_pk_mul_f32 v[98:99], v[98:99], v[8:9] op_sel_hi:[1,0]
	v_pk_mul_f32 v[96:97], v[96:97], v[8:9] op_sel_hi:[1,0]
	v_pk_mul_f32 v[94:95], v[94:95], v[8:9] op_sel_hi:[1,0]
	v_pk_mul_f32 v[92:93], v[92:93], v[8:9] op_sel_hi:[1,0]
	v_pk_mul_f32 v[90:91], v[90:91], v[8:9] op_sel_hi:[1,0]
	v_pk_mul_f32 v[88:89], v[88:89], v[8:9] op_sel_hi:[1,0]
	v_pk_mul_f32 v[86:87], v[86:87], v[8:9] op_sel_hi:[1,0]
	v_pk_mul_f32 v[84:85], v[84:85], v[8:9] op_sel_hi:[1,0]
	v_pk_mul_f32 v[82:83], v[82:83], v[8:9] op_sel_hi:[1,0]
	v_pk_mul_f32 v[80:81], v[80:81], v[8:9] op_sel_hi:[1,0]
	v_pk_mul_f32 v[78:79], v[78:79], v[8:9] op_sel_hi:[1,0]
	v_pk_mul_f32 v[76:77], v[76:77], v[8:9] op_sel_hi:[1,0]
	v_pk_mul_f32 v[74:75], v[74:75], v[8:9] op_sel_hi:[1,0]
	v_pk_mul_f32 v[72:73], v[72:73], v[8:9] op_sel_hi:[1,0]
	v_pk_mul_f32 v[70:71], v[70:71], v[8:9] op_sel_hi:[1,0]
	v_pk_mul_f32 v[68:69], v[68:69], v[8:9] op_sel_hi:[1,0]
	v_pk_mul_f32 v[66:67], v[66:67], v[8:9] op_sel_hi:[1,0]
	v_pk_mul_f32 v[64:65], v[64:65], v[8:9] op_sel_hi:[1,0]
	v_pk_mul_f32 v[62:63], v[62:63], v[8:9] op_sel_hi:[1,0]
	v_pk_mul_f32 v[60:61], v[60:61], v[8:9] op_sel_hi:[1,0]
	v_pk_mul_f32 v[58:59], v[58:59], v[8:9] op_sel_hi:[1,0]
	v_pk_mul_f32 v[56:57], v[56:57], v[8:9] op_sel_hi:[1,0]
	v_pk_mul_f32 v[54:55], v[54:55], v[8:9] op_sel_hi:[1,0]
	v_pk_mul_f32 v[52:53], v[52:53], v[8:9] op_sel_hi:[1,0]
	v_pk_mul_f32 v[50:51], v[50:51], v[8:9] op_sel_hi:[1,0]
	s_branch .LBB0_1272

; DI unsigned pk_bf16(float a, float b) { f32x2 v = {a, b}; bf2_t r = __builtin_convertvector(v, bf2_t); return __builtin_bit_cast(unsigned, r); }
; DI float xhalf_max(float v) { const auto r = __builtin_amdgcn_permlane32_swap(__float_as_uint(v), __float_as_uint(v), false, false); return fmaxf(__uint_as_float(r[0]), __uint_as_float(r[1])); }
;     ...
;             float mx = s[0][0];
; #pragma unroll
;             for (int i = 1; i < 16; ++i) mx = fmaxf(mx, s[0][i]);
; #pragma unroll
;             for (int i = 0; i < 16; ++i) mx = fmaxf(mx, s[1][i]);
;             mx = xhalf_max(mx);
;             const float mabs = mi + mx;
;             const bool up = mabs > m + 8.0f;
;             const float mn = up ? __uint_as_float(pk_bf16(mabs, 0.f) << 16) : m;
;             const float shift = mn - mi;
;             if (__ballot(shift != 0.f) != 0) {
;                 if (__ballot(up) != 0) {
;                     const float alpha = __builtin_amdgcn_exp2f(m - mn);
;                     l *= alpha;
; #pragma unroll
;                     for (int db = 0; db < DVB; ++db)
; #pragma unroll
;                         for (int i = 0; i < 16; ++i) o[db][i] *= alpha;
;                     m = mn;
.LBB0_1286:
	s_or_b64 exec, exec, s[52:53]
	v_max_f32_e32 v2, v35, v35
	v_max_f32_e32 v4, v34, v34
	v_max_f32_e32 v2, v4, v2
	v_max3_f32 v2, v2, v36, v37
	v_max3_f32 v2, v2, v38, v39
	v_max3_f32 v2, v2, v40, v41
	v_max3_f32 v2, v2, v42, v43
	v_max3_f32 v2, v2, v44, v45
	v_max3_f32 v2, v2, v46, v47
	v_max3_f32 v2, v2, v48, v49
	v_max3_f32 v2, v2, v18, v19
	v_max3_f32 v2, v2, v20, v21
	v_max3_f32 v2, v2, v22, v23
	v_max3_f32 v2, v2, v24, v25
	v_max3_f32 v2, v2, v26, v27
	v_max3_f32 v2, v2, v28, v29
	v_max3_f32 v2, v2, v30, v31
	v_max3_f32 v2, v2, v32, v33
	v_mov_b32_e32 v4, v2
	s_nop 1
	v_permlane32_swap_b32_e32 v2, v4
	v_max_f32_e32 v198, v2, v4
	v_mov_b32_e32 v209, v207
	v_pk_add_f32 v[4:5], v[208:209], v[198:199]
	s_nop 0
	v_cvt_pk_bf16_f32 v2, v4, 0
	v_lshlrev_b32_e32 v2, 16, v2
	v_cmp_gt_f32_e64 s[8:9], v4, v5
	s_nop 1
	v_cndmask_b32_e64 v4, v207, v2, s[8:9]
	v_sub_f32_e32 v2, v4, v208
	v_cmp_neq_f32_e32 vcc, 0, v2
	s_cbranch_vccz .LBB0_1291
	v_cndmask_b32_e64 v5, 0, 1, s[8:9]
	v_cmp_ne_u32_e32 vcc, 0, v5
	s_cbranch_vccz .LBB0_1289
	v_sub_f32_e32 v5, v207, v4
	v_exp_f32_e32 v8, v5
	s_nop 0
	v_mul_f32_e32 v6, v6, v8
	v_pk_mul_f32 v[112:113], v[112:113], v[8:9] op_sel_hi:[1,0]
	v_pk_mul_f32 v[110:111], v[110:111], v[8:9] op_sel_hi:[1,0]
	v_pk_mul_f32 v[108:109], v[108:109], v[8:9] op_sel_hi:[1,0]
	v_pk_mul_f32 v[106:107], v[106:107], v[8:9] op_sel_hi:[1,0]
	v_pk_mul_f32 v[104:105], v[104:105], v[8:9] op_sel_hi:[1,0]
	v_pk_mul_f32 v[102:103], v[102:103], v[8:9] op_sel_hi:[1,0]
	v_pk_mul_f32 v[100:101], v[100:101], v[8:9] op_sel_hi:[1,0]
	v_pk_mul_f32 v[98:99], v[98:99], v[8:9] op_sel_hi:[1,0]
	v_pk_mul_f32 v[96:97], v[96:97], v[8:9] op_sel_hi:[1,0]
	v_pk_mul_f32 v[94:95], v[94:95], v[8:9] op_sel_hi:[1,0]
	v_pk_mul_f32 v[92:93], v[92:93], v[8:9] op_sel_hi:[1,0]
	v_pk_mul_f32 v[90:91], v[90:91], v[8:9] op_sel_hi:[1,0]
	v_pk_mul_f32 v[88:89], v[88:89], v[8:9] op_sel_hi:[1,0]
	v_pk_mul_f32 v[86:87], v[86:87], v[8:9] op_sel_hi:[1,0]
	v_pk_mul_f32 v[84:85], v[84:85], v[8:9] op_sel_hi:[1,0]
	v_pk_mul_f32 v[82:83], v[82:83], v[8:9] op_sel_hi:[1,0]
	v_pk_mul_f32 v[80:81], v[80:81], v[8:9] op_sel_hi:[1,0]
	v_pk_mul_f32 v[78:79], v[78:79], v[8:9] op_sel_hi:[1,0]
	v_pk_mul_f32 v[76:77], v[76:77], v[8:9] op_sel_hi:[1,0]
	v_pk_mul_f32 v[74:75], v[74:75], v[8:9] op_sel_hi:[1,0]
	v_pk_mul_f32 v[72:73], v[72:73], v[8:9] op_sel_hi:[1,0]
	v_pk_mul_f32 v[70:71], v[70:71], v[8:9] op_sel_hi:[1,0]
	v_pk_mul_f32 v[68:69], v[68:69], v[8:9] op_sel_hi:[1,0]
	v_pk_mul_f32 v[66:67], v[66:67], v[8:9] op_sel_hi:[1,0]
	v_pk_mul_f32 v[64:65], v[64:65], v[8:9] op_sel_hi:[1,0]
	v_pk_mul_f32 v[62:63], v[62:63], v[8:9] op_sel_hi:[1,0]
	v_pk_mul_f32 v[60:61], v[60:61], v[8:9] op_sel_hi:[1,0]
	v_pk_mul_f32 v[58:59], v[58:59], v[8:9] op_sel_hi:[1,0]
	v_pk_mul_f32 v[56:57], v[56:57], v[8:9] op_sel_hi:[1,0]
	v_pk_mul_f32 v[54:55], v[54:55], v[8:9] op_sel_hi:[1,0]
	v_pk_mul_f32 v[52:53], v[52:53], v[8:9] op_sel_hi:[1,0]
	v_pk_mul_f32 v[50:51], v[50:51], v[8:9] op_sel_hi:[1,0]
	s_branch .LBB0_1290

; DI unsigned pk_bf16(float a, float b) { f32x2 v = {a, b}; bf2_t r = __builtin_convertvector(v, bf2_t); return __builtin_bit_cast(unsigned, r); }
; DI float xhalf_max(float v) { const auto r = __builtin_amdgcn_permlane32_swap(__float_as_uint(v), __float_as_uint(v), false, false); return fmaxf(__uint_as_float(r[0]), __uint_as_float(r[1])); }
;     ...
;             float mx = s[0][0];
; #pragma unroll
;             for (int i = 1; i < 16; ++i) mx = fmaxf(mx, s[0][i]);
; #pragma unroll
;             for (int i = 0; i < 16; ++i) mx = fmaxf(mx, s[1][i]);
;             mx = xhalf_max(mx);
;             const float mabs = mi + mx;
;             const bool up = mabs > m + 8.0f;
;             const float mn = up ? __uint_as_float(pk_bf16(mabs, 0.f) << 16) : m;
;             const float shift = mn - mi;
;             if (__ballot(shift != 0.f) != 0) {
;                 if (__ballot(up) != 0) {
;                     const float alpha = __builtin_amdgcn_exp2f(m - mn);
;                     l *= alpha;
; #pragma unroll
;                     for (int db = 0; db < DVB; ++db)
; #pragma unroll
;                         for (int i = 0; i < 16; ++i) o[db][i] *= alpha;
;                     m = mn;
.LBB0_1361:
	s_or_b64 exec, exec, s[8:9]
	v_max_f32_e32 v2, v19, v19
	v_max_f32_e32 v36, v18, v18
	v_max_f32_e32 v2, v36, v2
	v_max3_f32 v2, v2, v20, v21
	v_max3_f32 v2, v2, v22, v23
	v_max3_f32 v2, v2, v24, v25
	v_max3_f32 v2, v2, v26, v27
	v_max3_f32 v2, v2, v28, v29
	v_max3_f32 v2, v2, v30, v31
	v_max3_f32 v2, v2, v32, v33
	v_max3_f32 v2, v2, v34, v35
	v_max3_f32 v2, v2, v16, v17
	v_max3_f32 v2, v2, v14, v15
	v_max3_f32 v2, v2, v12, v13
	v_max3_f32 v2, v2, v10, v11
	v_max3_f32 v2, v2, v6, v7
	v_max3_f32 v2, v2, v8, v9
	v_max3_f32 v2, v2, v4, v5
	v_mov_b32_e32 v36, v2
	s_nop 1
	v_permlane32_swap_b32_e32 v2, v36
	v_max_f32_e32 v158, v2, v36
	v_pk_add_f32 v[36:37], v[166:167], v[158:159]
	s_nop 0
	v_cvt_pk_bf16_f32 v2, v36, 0
	v_lshlrev_b32_e32 v2, 16, v2
	v_cmp_gt_f32_e64 s[8:9], v36, v37
	s_nop 1
	v_cndmask_b32_e64 v36, v167, v2, s[8:9]
	v_sub_f32_e32 v2, v36, v166
	v_cmp_neq_f32_e32 vcc, 0, v2
	s_cbranch_vccz .LBB0_1366
	v_cndmask_b32_e64 v37, 0, 1, s[8:9]
	v_cmp_ne_u32_e32 vcc, 0, v37
	s_cbranch_vccz .LBB0_1364
	v_sub_f32_e32 v37, v167, v36
	v_exp_f32_e32 v38, v37
	s_nop 0
	v_mul_f32_e32 v192, v192, v38
	v_pk_mul_f32 v[96:97], v[96:97], v[38:39] op_sel_hi:[1,0]
	v_pk_mul_f32 v[94:95], v[94:95], v[38:39] op_sel_hi:[1,0]
	v_pk_mul_f32 v[92:93], v[92:93], v[38:39] op_sel_hi:[1,0]
	v_pk_mul_f32 v[90:91], v[90:91], v[38:39] op_sel_hi:[1,0]
	v_pk_mul_f32 v[88:89], v[88:89], v[38:39] op_sel_hi:[1,0]
	v_pk_mul_f32 v[86:87], v[86:87], v[38:39] op_sel_hi:[1,0]
	v_pk_mul_f32 v[84:85], v[84:85], v[38:39] op_sel_hi:[1,0]
	v_pk_mul_f32 v[82:83], v[82:83], v[38:39] op_sel_hi:[1,0]
	v_pk_mul_f32 v[80:81], v[80:81], v[38:39] op_sel_hi:[1,0]
	v_pk_mul_f32 v[78:79], v[78:79], v[38:39] op_sel_hi:[1,0]
	v_pk_mul_f32 v[76:77], v[76:77], v[38:39] op_sel_hi:[1,0]
	v_pk_mul_f32 v[74:75], v[74:75], v[38:39] op_sel_hi:[1,0]
	v_pk_mul_f32 v[72:73], v[72:73], v[38:39] op_sel_hi:[1,0]
	v_pk_mul_f32 v[70:71], v[70:71], v[38:39] op_sel_hi:[1,0]
	v_pk_mul_f32 v[68:69], v[68:69], v[38:39] op_sel_hi:[1,0]
	v_pk_mul_f32 v[66:67], v[66:67], v[38:39] op_sel_hi:[1,0]
	s_branch .LBB0_1365

; DI unsigned pk_bf16(float a, float b) { f32x2 v = {a, b}; bf2_t r = __builtin_convertvector(v, bf2_t); return __builtin_bit_cast(unsigned, r); }
; DI float xhalf_max(float v) { const auto r = __builtin_amdgcn_permlane32_swap(__float_as_uint(v), __float_as_uint(v), false, false); return fmaxf(__uint_as_float(r[0]), __uint_as_float(r[1])); }
;     ...
;             float mx = s[0][0];
; #pragma unroll
;             for (int i = 1; i < 16; ++i) mx = fmaxf(mx, s[0][i]);
; #pragma unroll
;             for (int i = 0; i < 16; ++i) mx = fmaxf(mx, s[1][i]);
;             mx = xhalf_max(mx);
;             const float mabs = mi + mx;
;             const bool up = mabs > m + 8.0f;
;             const float mn = up ? __uint_as_float(pk_bf16(mabs, 0.f) << 16) : m;
;             const float shift = mn - mi;
;             if (__ballot(shift != 0.f) != 0) {
;                 if (__ballot(up) != 0) {
;                     const float alpha = __builtin_amdgcn_exp2f(m - mn);
;                     l *= alpha;
; #pragma unroll
;                     for (int db = 0; db < DVB; ++db)
; #pragma unroll
;                         for (int i = 0; i < 16; ++i) o[db][i] *= alpha;
;                     m = mn;
.LBB0_1382:
	s_or_b64 exec, exec, s[6:7]
	v_max_f32_e32 v2, v51, v51
	v_max_f32_e32 v100, v50, v50
	v_max_f32_e32 v2, v100, v2
	v_max3_f32 v2, v2, v52, v53
	v_max3_f32 v2, v2, v54, v55
	v_max3_f32 v2, v2, v56, v57
	v_max3_f32 v2, v2, v58, v59
	v_max3_f32 v2, v2, v60, v61
	v_max3_f32 v2, v2, v62, v63
	v_max3_f32 v2, v2, v64, v65
	v_max3_f32 v2, v2, v98, v99
	v_max3_f32 v2, v2, v16, v17
	v_max3_f32 v2, v2, v14, v15
	v_max3_f32 v2, v2, v12, v13
	v_max3_f32 v2, v2, v10, v11
	v_max3_f32 v2, v2, v8, v9
	v_max3_f32 v2, v2, v6, v7
	v_max3_f32 v2, v2, v4, v5
	v_mov_b32_e32 v100, v2
	s_nop 1
	v_permlane32_swap_b32_e32 v2, v100
	v_max_f32_e32 v158, v2, v100
	v_mov_b32_e32 v169, v167
	v_pk_add_f32 v[100:101], v[168:169], v[158:159]
	s_nop 0
	v_cvt_pk_bf16_f32 v2, v100, 0
	v_lshlrev_b32_e32 v2, 16, v2
	v_cmp_gt_f32_e64 s[6:7], v100, v101
	s_nop 1
	v_cndmask_b32_e64 v100, v167, v2, s[6:7]
	v_sub_f32_e32 v2, v100, v168
	v_cmp_neq_f32_e32 vcc, 0, v2
	s_cbranch_vccz .LBB0_1387
	v_cndmask_b32_e64 v101, 0, 1, s[6:7]
	v_cmp_ne_u32_e32 vcc, 0, v101
	s_cbranch_vccz .LBB0_1385
	v_sub_f32_e32 v101, v167, v100
	v_exp_f32_e32 v102, v101
	s_nop 0
	v_mul_f32_e32 v192, v192, v102
	v_pk_mul_f32 v[96:97], v[96:97], v[102:103] op_sel_hi:[1,0]
	v_pk_mul_f32 v[94:95], v[94:95], v[102:103] op_sel_hi:[1,0]
	v_pk_mul_f32 v[92:93], v[92:93], v[102:103] op_sel_hi:[1,0]
	v_pk_mul_f32 v[90:91], v[90:91], v[102:103] op_sel_hi:[1,0]
	v_pk_mul_f32 v[88:89], v[88:89], v[102:103] op_sel_hi:[1,0]
	v_pk_mul_f32 v[86:87], v[86:87], v[102:103] op_sel_hi:[1,0]
	v_pk_mul_f32 v[84:85], v[84:85], v[102:103] op_sel_hi:[1,0]
	v_pk_mul_f32 v[82:83], v[82:83], v[102:103] op_sel_hi:[1,0]
	v_pk_mul_f32 v[80:81], v[80:81], v[102:103] op_sel_hi:[1,0]
	v_pk_mul_f32 v[78:79], v[78:79], v[102:103] op_sel_hi:[1,0]
	v_pk_mul_f32 v[76:77], v[76:77], v[102:103] op_sel_hi:[1,0]
	v_pk_mul_f32 v[74:75], v[74:75], v[102:103] op_sel_hi:[1,0]
	v_pk_mul_f32 v[72:73], v[72:73], v[102:103] op_sel_hi:[1,0]
	v_pk_mul_f32 v[70:71], v[70:71], v[102:103] op_sel_hi:[1,0]
	v_pk_mul_f32 v[68:69], v[68:69], v[102:103] op_sel_hi:[1,0]
	v_pk_mul_f32 v[66:67], v[66:67], v[102:103] op_sel_hi:[1,0]
	s_branch .LBB0_1386

; DI unsigned pk_bf16(float a, float b) { f32x2 v = {a, b}; bf2_t r = __builtin_convertvector(v, bf2_t); return __builtin_bit_cast(unsigned, r); }
; DI int crow(int i, int hh) { return (i & 3) + 8 * (i >> 2) + 4 * hh; }
; DI float xhalf_max(float v) { const auto r = __builtin_amdgcn_permlane32_swap(__float_as_uint(v), __float_as_uint(v), false, false); return fmaxf(__uint_as_float(r[0]), __uint_as_float(r[1])); }
;     ...
;             if (MODE == 2) {
;                 const u64 wsh = wcur >> (4 * hh);
;                 const int wlo = (int)(unsigned)wsh, whi = (int)(unsigned)(wsh >> 32);
; #pragma unroll
;                 for (int i = 0; i < 16; ++i) {
;                     const int bit = (i & 3) + 8 * (i >> 2);
;                     const unsigned m0 = (unsigned)__builtin_amdgcn_sbfe(wlo, bit, 1), m1 = (unsigned)__builtin_amdgcn_sbfe(whi, bit, 1);
;                     s[0][i] = __uint_as_float((__float_as_uint(s[0][i]) & m0) | (0xff800000u & ~m0));
;                     s[1][i] = __uint_as_float((__float_as_uint(s[1][i]) & m1) | (0xff800000u & ~m1));
;                 }
;             } else if (k0 + 63 > qw0) {
; #pragma unroll
;                 for (int blk = 0; blk < 2; ++blk)
; #pragma unroll
;                     for (int i = 0; i < 16; ++i) { const int key = k0 + 32 * blk + crow(i, hh); if (key > myq) s[blk][i] = -INFINITY; }
;             }
;             float mx = s[0][0];
; #pragma unroll
;             for (int i = 1; i < 16; ++i) mx = fmaxf(mx, s[0][i]);
; #pragma unroll
;             for (int i = 0; i < 16; ++i) mx = fmaxf(mx, s[1][i]);
;             mx = xhalf_max(mx);
;             const float mabs = mi + mx;
;             const bool up = mabs > m + 8.0f;
;             const float mn = up ? __uint_as_float(pk_bf16(mabs, 0.f) << 16) : m;
.LBB0_3611:
	s_or_b64 exec, exec, s[26:27]
	v_cmp_le_i32_e32 vcc, s44, v175
	s_and_saveexec_b64 s[26:27], vcc
	s_cbranch_execz .LBB0_3618
	v_lshrrev_b64 v[6:7], v170, v[116:117]
	v_bfe_i32 v1, v6, 0, 1
	v_bitop3_b32 v18, v18, s34, v1 bitop3:0xe4
	v_bfe_i32 v1, v6, 1, 1
	v_bfe_i32 v4, v7, 1, 1
	v_bfe_i32 v2, v7, 0, 1
	v_bitop3_b32 v19, v19, s34, v1 bitop3:0xe4
	v_bitop3_b32 v1, v35, s34, v4 bitop3:0xe4
	v_bfe_i32 v4, v6, 2, 1
	v_bfe_i32 v5, v7, 2, 1
	v_bitop3_b32 v2, v34, s34, v2 bitop3:0xe4
	v_bitop3_b32 v20, v20, s34, v4 bitop3:0xe4
	v_bitop3_b32 v4, v36, s34, v5 bitop3:0xe4
	v_bfe_i32 v5, v6, 3, 1
	v_bfe_i32 v8, v7, 3, 1
	v_bfe_i32 v10, v6, 11, 1
	v_bfe_i32 v34, v6, 18, 1
	v_bfe_i32 v35, v7, 18, 1
	v_bitop3_b32 v21, v21, s34, v5 bitop3:0xe4
	v_bitop3_b32 v17, v37, s34, v8 bitop3:0xe4
	v_bfe_i32 v5, v6, 8, 1
	v_bfe_i32 v8, v7, 8, 1
	v_bitop3_b32 v25, v25, s34, v10 bitop3:0xe4
	v_bitop3_b32 v28, v28, s34, v34 bitop3:0xe4
	v_bitop3_b32 v10, v44, s34, v35 bitop3:0xe4
	v_bitop3_b32 v22, v22, s34, v5 bitop3:0xe4
	v_bitop3_b32 v16, v38, s34, v8 bitop3:0xe4
	v_bfe_i32 v5, v6, 9, 1
	v_bfe_i32 v8, v7, 9, 1
	v_max_f32_e32 v34, v18, v19
	v_bitop3_b32 v23, v23, s34, v5 bitop3:0xe4
	v_bitop3_b32 v5, v39, s34, v8 bitop3:0xe4
	v_bfe_i32 v8, v6, 10, 1
	v_max3_f32 v34, v34, v20, v21
	v_bfe_i32 v12, v6, 16, 1
	v_bfe_i32 v14, v6, 17, 1
	v_bitop3_b32 v24, v24, s34, v8 bitop3:0xe4
	v_max3_f32 v34, v34, v22, v23
	v_bfe_i32 v36, v6, 19, 1
	v_bitop3_b32 v26, v26, s34, v12 bitop3:0xe4
	v_bitop3_b32 v27, v27, s34, v14 bitop3:0xe4
	v_max3_f32 v34, v34, v24, v25
	v_bfe_i32 v38, v6, 24, 1
	v_bfe_i32 v114, v6, 25, 1
	v_bitop3_b32 v29, v29, s34, v36 bitop3:0xe4
	v_max3_f32 v34, v34, v26, v27
	v_bfe_i32 v116, v6, 26, 1
	v_bfe_i32 v118, v6, 27, 1
	v_bitop3_b32 v30, v30, s34, v38 bitop3:0xe4
	v_bitop3_b32 v31, v31, s34, v114 bitop3:0xe4
	v_max3_f32 v34, v34, v28, v29
	v_bitop3_b32 v32, v32, s34, v116 bitop3:0xe4
	v_bitop3_b32 v33, v33, s34, v118 bitop3:0xe4
	v_max3_f32 v34, v34, v30, v31
	v_max3_f32 v34, v34, v32, v33
	v_max3_f32 v34, v34, v2, v1
	v_bfe_i32 v9, v7, 10, 1
	v_bfe_i32 v11, v7, 11, 1
	v_max3_f32 v34, v34, v4, v17
	v_bfe_i32 v13, v7, 16, 1
	v_bfe_i32 v15, v7, 17, 1
	v_bfe_i32 v37, v7, 19, 1
	v_bfe_i32 v39, v7, 24, 1
	v_bfe_i32 v115, v7, 25, 1
	v_bfe_i32 v117, v7, 26, 1
	v_bfe_i32 v119, v7, 27, 1
	v_bitop3_b32 v6, v40, s34, v9 bitop3:0xe4
	v_bitop3_b32 v7, v41, s34, v11 bitop3:0xe4
	v_max3_f32 v34, v34, v16, v5
	v_bitop3_b32 v8, v42, s34, v13 bitop3:0xe4
	v_bitop3_b32 v9, v43, s34, v15 bitop3:0xe4
	v_max3_f32 v34, v34, v6, v7
	v_bitop3_b32 v11, v45, s34, v37 bitop3:0xe4
	v_max3_f32 v34, v34, v8, v9
	v_bitop3_b32 v12, v46, s34, v39 bitop3:0xe4
	v_bitop3_b32 v13, v47, s34, v115 bitop3:0xe4
	v_max3_f32 v34, v34, v10, v11
	v_bitop3_b32 v14, v48, s34, v117 bitop3:0xe4
	v_bitop3_b32 v15, v49, s34, v119 bitop3:0xe4
	v_max3_f32 v34, v34, v12, v13
	v_max3_f32 v34, v34, v14, v15
	v_mov_b32_e32 v35, v34
	s_nop 1
	v_permlane32_swap_b32_e32 v34, v35
	v_max_f32_e32 v176, v34, v35
	v_pk_add_f32 v[34:35], v[182:183], v[176:177]
	s_nop 0
	v_cvt_pk_bf16_f32 v36, v34, 0
	v_lshlrev_b32_e32 v36, 16, v36
	v_cmp_gt_f32_e64 s[4:5], v34, v35
	s_nop 1
	v_cndmask_b32_e64 v189, v183, v36, s[4:5]
	v_sub_f32_e32 v176, v189, v182
	v_cmp_neq_f32_e32 vcc, 0, v176
	s_cbranch_vccz .LBB0_3617

; DI unsigned pk_bf16(float a, float b) { f32x2 v = {a, b}; bf2_t r = __builtin_convertvector(v, bf2_t); return __builtin_bit_cast(unsigned, r); }
; DI int crow(int i, int hh) { return (i & 3) + 8 * (i >> 2) + 4 * hh; }
; DI float xhalf_max(float v) { const auto r = __builtin_amdgcn_permlane32_swap(__float_as_uint(v), __float_as_uint(v), false, false); return fmaxf(__uint_as_float(r[0]), __uint_as_float(r[1])); }
;     ...
;             if (MODE == 2) {
;                 const u64 wsh = wcur >> (4 * hh);
;                 const int wlo = (int)(unsigned)wsh, whi = (int)(unsigned)(wsh >> 32);
; #pragma unroll
;                 for (int i = 0; i < 16; ++i) {
;                     const int bit = (i & 3) + 8 * (i >> 2);
;                     const unsigned m0 = (unsigned)__builtin_amdgcn_sbfe(wlo, bit, 1), m1 = (unsigned)__builtin_amdgcn_sbfe(whi, bit, 1);
;                     s[0][i] = __uint_as_float((__float_as_uint(s[0][i]) & m0) | (0xff800000u & ~m0));
;                     s[1][i] = __uint_as_float((__float_as_uint(s[1][i]) & m1) | (0xff800000u & ~m1));
;                 }
;             } else if (k0 + 63 > qw0) {
; #pragma unroll
;                 for (int blk = 0; blk < 2; ++blk)
; #pragma unroll
;                     for (int i = 0; i < 16; ++i) { const int key = k0 + 32 * blk + crow(i, hh); if (key > myq) s[blk][i] = -INFINITY; }
;             }
;             float mx = s[0][0];
; #pragma unroll
;             for (int i = 1; i < 16; ++i) mx = fmaxf(mx, s[0][i]);
; #pragma unroll
;             for (int i = 0; i < 16; ++i) mx = fmaxf(mx, s[1][i]);
;             mx = xhalf_max(mx);
;             const float mabs = mi + mx;
;             const bool up = mabs > m + 8.0f;
;             const float mn = up ? __uint_as_float(pk_bf16(mabs, 0.f) << 16) : m;
.LBB0_3627:
	s_or_b64 exec, exec, s[24:25]
	s_add_i32 s0, s44, 64
	v_cmp_le_i32_e32 vcc, s0, v175
	s_and_saveexec_b64 s[24:25], vcc
	s_cbranch_execz .LBB0_3636
	v_lshrrev_b64 v[6:7], v170, v[192:193]
	v_bfe_i32 v10, v6, 3, 1
	v_bfe_i32 v1, v6, 0, 1
	v_bitop3_b32 v17, v53, s34, v10 bitop3:0xe4
	v_bfe_i32 v10, v6, 8, 1
	v_bitop3_b32 v2, v50, s34, v1 bitop3:0xe4
	v_bfe_i32 v1, v6, 1, 1
	v_bitop3_b32 v16, v54, s34, v10 bitop3:0xe4
	v_bfe_i32 v10, v6, 9, 1
	v_bfe_i32 v8, v7, 1, 1
	v_bitop3_b32 v1, v51, s34, v1 bitop3:0xe4
	v_bfe_i32 v9, v7, 2, 1
	v_bitop3_b32 v55, v55, s34, v10 bitop3:0xe4
	v_bfe_i32 v10, v6, 10, 1
	v_bfe_i32 v50, v7, 16, 1
	v_bfe_i32 v51, v7, 17, 1
	v_bfe_i32 v4, v6, 2, 1
	v_bitop3_b32 v56, v56, s34, v10 bitop3:0xe4
	v_bfe_i32 v10, v6, 11, 1
	v_bitop3_b32 v67, v67, s34, v8 bitop3:0xe4
	v_bitop3_b32 v68, v68, s34, v9 bitop3:0xe4
	v_bitop3_b32 v8, v74, s34, v50 bitop3:0xe4
	v_bitop3_b32 v9, v75, s34, v51 bitop3:0xe4
	v_bitop3_b32 v4, v52, s34, v4 bitop3:0xe4
	v_bitop3_b32 v57, v57, s34, v10 bitop3:0xe4
	v_bfe_i32 v10, v6, 16, 1
	v_max_f32_e32 v50, v2, v1
	v_bitop3_b32 v58, v58, s34, v10 bitop3:0xe4
	v_bfe_i32 v10, v6, 17, 1
	v_max3_f32 v50, v50, v4, v17
	v_bitop3_b32 v59, v59, s34, v10 bitop3:0xe4
	v_bfe_i32 v10, v6, 18, 1
	v_max3_f32 v50, v50, v16, v55
	v_bitop3_b32 v60, v60, s34, v10 bitop3:0xe4
	v_bfe_i32 v10, v6, 19, 1
	v_max3_f32 v50, v50, v56, v57
	v_bfe_i32 v54, v6, 24, 1
	v_bfe_i32 v117, v6, 25, 1
	v_bitop3_b32 v61, v61, s34, v10 bitop3:0xe4
	v_max3_f32 v50, v50, v58, v59
	v_bfe_i32 v119, v6, 26, 1
	v_bfe_i32 v6, v6, 27, 1
	v_bitop3_b32 v62, v62, s34, v54 bitop3:0xe4
	v_bitop3_b32 v63, v63, s34, v117 bitop3:0xe4
	v_max3_f32 v50, v50, v60, v61
	v_bfe_i32 v5, v7, 0, 1
	v_bitop3_b32 v64, v64, s34, v119 bitop3:0xe4
	v_bitop3_b32 v65, v65, s34, v6 bitop3:0xe4
	v_max3_f32 v50, v50, v62, v63
	v_bfe_i32 v11, v7, 3, 1
	v_bitop3_b32 v66, v66, s34, v5 bitop3:0xe4
	v_max3_f32 v50, v50, v64, v65
	v_bfe_i32 v12, v7, 8, 1
	v_bfe_i32 v13, v7, 9, 1
	v_bitop3_b32 v69, v69, s34, v11 bitop3:0xe4
	v_max3_f32 v50, v50, v66, v67
	v_bfe_i32 v14, v7, 10, 1
	v_bfe_i32 v15, v7, 11, 1
	v_bitop3_b32 v70, v70, s34, v12 bitop3:0xe4
	v_bitop3_b32 v5, v71, s34, v13 bitop3:0xe4
	v_max3_f32 v50, v50, v68, v69
	v_bfe_i32 v52, v7, 18, 1
	v_bfe_i32 v53, v7, 19, 1
	v_bfe_i32 v116, v7, 24, 1
	v_bfe_i32 v118, v7, 25, 1
	v_bfe_i32 v120, v7, 26, 1
	v_bfe_i32 v121, v7, 27, 1
	v_bitop3_b32 v6, v72, s34, v14 bitop3:0xe4
	v_bitop3_b32 v7, v73, s34, v15 bitop3:0xe4
	v_max3_f32 v50, v50, v70, v5
	v_max3_f32 v50, v50, v6, v7
	v_bitop3_b32 v10, v76, s34, v52 bitop3:0xe4
	v_bitop3_b32 v11, v77, s34, v53 bitop3:0xe4
	v_max3_f32 v50, v50, v8, v9
	v_bitop3_b32 v12, v78, s34, v116 bitop3:0xe4
	v_bitop3_b32 v13, v79, s34, v118 bitop3:0xe4
	v_max3_f32 v50, v50, v10, v11
	v_bitop3_b32 v14, v80, s34, v120 bitop3:0xe4
	v_bitop3_b32 v15, v81, s34, v121 bitop3:0xe4
	v_max3_f32 v50, v50, v12, v13
	v_max3_f32 v50, v50, v14, v15
	v_mov_b32_e32 v51, v50
	s_nop 1
	v_permlane32_swap_b32_e32 v50, v51
	v_max_f32_e32 v176, v50, v51
	v_mov_b32_e32 v189, v183
	v_pk_add_f32 v[50:51], v[188:189], v[176:177]
	s_nop 0
	v_cvt_pk_bf16_f32 v52, v50, 0
	v_lshlrev_b32_e32 v52, 16, v52
	v_cmp_gt_f32_e64 s[6:7], v50, v51
	s_nop 1
	v_cndmask_b32_e64 v50, v183, v52, s[6:7]
	v_sub_f32_e32 v51, v50, v188
	v_cmp_neq_f32_e32 vcc, 0, v51
	s_cbranch_vccz .LBB0_3635

;     ...
;         auto qk = [&](f32x16 (&s)[2], float& mi, int stg) {
;             const unsigned char* kb_ = lds + stg * STG + koff;
;             const unsigned mb = pk_bf16((m > -1e29f) ? -m : 0.f, 0.f) & 0xffffu;
;             mi = -__uint_as_float(mb << 16);
;             u32x4 qxw; qxw.x = hh ? 0u : mb; qxw.y = 0u; qxw.z = 0u; qxw.w = 0u;
;             u32x4 kxw; kxw.x = hh ? 0u : 0x3f80u; kxw.y = 0u; kxw.z = 0u; kxw.w = 0u;
;             const bf16x8 qx = __builtin_bit_cast(bf16x8, qxw), kx = __builtin_bit_cast(bf16x8, kxw);
;             f32x16 zero;
; #pragma unroll
;             for (int i = 0; i < 16; ++i) zero[i] = 0.f;
; #pragma unroll
;             for (int blk = 0; blk < 2; ++blk) {
;                 s[blk] = MFMA32(kx, qx, zero);
; #pragma unroll
;                 for (int ks = 0; ks < 4; ++ks) {
;                     const bf16x8 kf = *(const bf16x8*)(kb_ + blk * 4608 + ks * 32);
;                     s[blk] = MFMA32(kf, qf[ks], s[blk]);
;                 }
;             }
;         };
;     ...
;             if (MODE == 2) {
;                 const u64 wsh = wcur >> (4 * hh);
;                 const int wlo = (int)(unsigned)wsh, whi = (int)(unsigned)(wsh >> 32);
; #pragma unroll
;                 for (int i = 0; i < 16; ++i) {
;                     const int bit = (i & 3) + 8 * (i >> 2);
;                     const unsigned m0 = (unsigned)__builtin_amdgcn_sbfe(wlo, bit, 1), m1 = (unsigned)__builtin_amdgcn_sbfe(whi, bit, 1);
;                     s[0][i] = __uint_as_float((__float_as_uint(s[0][i]) & m0) | (0xff800000u & ~m0));
;                     s[1][i] = __uint_as_float((__float_as_uint(s[1][i]) & m1) | (0xff800000u & ~m1));
;                 }
;             } else if (k0 + 63 > qw0) {
; #pragma unroll
;                 for (int blk = 0; blk < 2; ++blk)
; #pragma unroll
;                     for (int i = 0; i < 16; ++i) { const int key = k0 + 32 * blk + crow(i, hh); if (key > myq) s[blk][i] = -INFINITY; }
;             }
;             float mx = s[0][0];
; #pragma unroll
;             for (int i = 1; i < 16; ++i) mx = fmaxf(mx, s[0][i]);
; #pragma unroll
;             for (int i = 0; i < 16; ++i) mx = fmaxf(mx, s[1][i]);
;             mx = xhalf_max(mx);
;             const float mabs = mi + mx;
;             const bool up = mabs > m + 8.0f;
;             const float mn = up ? __uint_as_float(pk_bf16(mabs, 0.f) << 16) : m;
.Lil1_fast:
	s_mov_b64 s[26:27], exec
	v_cmp_lt_f32_e64 s[4:5], s31, v183
	s_mov_b64 vcc, s[2:3]
	v_mov_b32_e32 v245, v3
	v_mov_b32_e32 v246, v3
	v_cndmask_b32_e64 v244, 0, -v183, s[4:5]
	v_cvt_pk_bf16_f32 v248, v244, 0
	v_cndmask_b32_sdwa v244, v3, v248, vcc dst_sel:DWORD dst_unused:UNUSED_PAD src0_sel:DWORD src1_sel:WORD_0
	v_mov_b32_e32 v247, v3
	v_lshlrev_b32_e32 v249, 16, v248
	v_xor_b32_e32 v188, 0x80000000, v249
	v_mfma_f32_32x32x16_bf16 v[66:81], v[130:133], v[244:247], 0
	v_lshrrev_b64 v[6:7], v170, v[116:117]
	v_bfe_i32 v1, v6, 0, 1
	v_bitop3_b32 v18, v18, s34, v1 bitop3:0xe4
	v_bfe_i32 v1, v6, 1, 1
	v_bfe_i32 v4, v7, 1, 1
	v_bfe_i32 v2, v7, 0, 1
	v_bitop3_b32 v19, v19, s34, v1 bitop3:0xe4
	v_bitop3_b32 v1, v35, s34, v4 bitop3:0xe4
	v_bfe_i32 v4, v6, 2, 1
	v_bfe_i32 v5, v7, 2, 1
	v_bitop3_b32 v2, v34, s34, v2 bitop3:0xe4
	s_waitcnt lgkmcnt(7)
	v_mfma_f32_32x32x16_bf16 v[50:65], v[212:215], v[142:145], v[66:81]
	v_bitop3_b32 v20, v20, s34, v4 bitop3:0xe4
	v_bitop3_b32 v4, v36, s34, v5 bitop3:0xe4
	v_bfe_i32 v5, v6, 3, 1
	v_bfe_i32 v8, v7, 3, 1
	v_bfe_i32 v10, v6, 11, 1
	v_bfe_i32 v34, v6, 18, 1
	v_bfe_i32 v35, v7, 18, 1
	v_bitop3_b32 v21, v21, s34, v5 bitop3:0xe4
	v_bitop3_b32 v17, v37, s34, v8 bitop3:0xe4
	v_bfe_i32 v5, v6, 8, 1
	s_waitcnt lgkmcnt(6)
	v_mfma_f32_32x32x16_bf16 v[50:65], v[216:219], v[146:149], v[50:65]
	v_bfe_i32 v8, v7, 8, 1
	v_bitop3_b32 v25, v25, s34, v10 bitop3:0xe4
	v_bitop3_b32 v28, v28, s34, v34 bitop3:0xe4
	v_bitop3_b32 v10, v44, s34, v35 bitop3:0xe4
	v_bitop3_b32 v22, v22, s34, v5 bitop3:0xe4
	v_bitop3_b32 v16, v38, s34, v8 bitop3:0xe4
	v_bfe_i32 v5, v6, 9, 1
	v_bfe_i32 v8, v7, 9, 1
	v_max_f32_e32 v34, v18, v19
	s_waitcnt lgkmcnt(5)
	v_mfma_f32_32x32x16_bf16 v[50:65], v[220:223], v[150:153], v[50:65]
	v_bitop3_b32 v23, v23, s34, v5 bitop3:0xe4
	v_bitop3_b32 v5, v39, s34, v8 bitop3:0xe4
	v_bfe_i32 v8, v6, 10, 1
	v_max3_f32 v34, v34, v20, v21
	v_bfe_i32 v12, v6, 16, 1
	v_bfe_i32 v14, v6, 17, 1
	v_bitop3_b32 v24, v24, s34, v8 bitop3:0xe4
	v_max3_f32 v34, v34, v22, v23
	v_bfe_i32 v36, v6, 19, 1
	v_bitop3_b32 v26, v26, s34, v12 bitop3:0xe4
	v_bitop3_b32 v27, v27, s34, v14 bitop3:0xe4
	s_waitcnt lgkmcnt(4)
	v_mfma_f32_32x32x16_bf16 v[50:65], v[224:227], v[154:157], v[50:65]
	v_max3_f32 v34, v34, v24, v25
	v_bfe_i32 v38, v6, 24, 1
	v_bfe_i32 v114, v6, 25, 1
	v_bitop3_b32 v29, v29, s34, v36 bitop3:0xe4
	v_max3_f32 v34, v34, v26, v27
	v_bfe_i32 v116, v6, 26, 1
	v_bfe_i32 v118, v6, 27, 1
	v_bitop3_b32 v30, v30, s34, v38 bitop3:0xe4
	v_bitop3_b32 v31, v31, s34, v114 bitop3:0xe4
	v_max3_f32 v34, v34, v28, v29
	s_waitcnt lgkmcnt(3)
	v_mfma_f32_32x32x16_bf16 v[66:81], v[228:231], v[142:145], v[66:81]
	v_bitop3_b32 v32, v32, s34, v116 bitop3:0xe4
	v_bitop3_b32 v33, v33, s34, v118 bitop3:0xe4
	v_max3_f32 v34, v34, v30, v31
	v_max3_f32 v34, v34, v32, v33
	v_max3_f32 v34, v34, v2, v1
	v_bfe_i32 v9, v7, 10, 1
	v_bfe_i32 v11, v7, 11, 1
	v_max3_f32 v34, v34, v4, v17
	v_bfe_i32 v13, v7, 16, 1
	v_bfe_i32 v15, v7, 17, 1
	v_bfe_i32 v37, v7, 19, 1
	s_waitcnt lgkmcnt(2)
	v_mfma_f32_32x32x16_bf16 v[66:81], v[232:235], v[146:149], v[66:81]
	v_bfe_i32 v39, v7, 24, 1
	v_bfe_i32 v115, v7, 25, 1
	v_bfe_i32 v117, v7, 26, 1
	v_bfe_i32 v119, v7, 27, 1
	v_bitop3_b32 v6, v40, s34, v9 bitop3:0xe4
	v_bitop3_b32 v7, v41, s34, v11 bitop3:0xe4
	v_max3_f32 v34, v34, v16, v5
	v_bitop3_b32 v8, v42, s34, v13 bitop3:0xe4
	v_bitop3_b32 v9, v43, s34, v15 bitop3:0xe4
	v_max3_f32 v34, v34, v6, v7
	v_bitop3_b32 v11, v45, s34, v37 bitop3:0xe4
	s_waitcnt lgkmcnt(1)
	v_mfma_f32_32x32x16_bf16 v[66:81], v[236:239], v[150:153], v[66:81]
	v_max3_f32 v34, v34, v8, v9
	v_bitop3_b32 v12, v46, s34, v39 bitop3:0xe4
	v_bitop3_b32 v13, v47, s34, v115 bitop3:0xe4
	v_max3_f32 v34, v34, v10, v11
	v_bitop3_b32 v14, v48, s34, v117 bitop3:0xe4
	v_bitop3_b32 v15, v49, s34, v119 bitop3:0xe4
	v_max3_f32 v34, v34, v12, v13
	v_max3_f32 v34, v34, v14, v15
	v_mov_b32_e32 v35, v34
	s_nop 1
	s_waitcnt lgkmcnt(0)
	v_mfma_f32_32x32x16_bf16 v[66:81], v[240:243], v[154:157], v[66:81]
	v_permlane32_swap_b32_e32 v34, v35
	v_max_f32_e32 v176, v34, v35
	v_pk_add_f32 v[34:35], v[182:183], v[176:177]
	s_nop 0
	v_cvt_pk_bf16_f32 v36, v34, 0
	v_lshlrev_b32_e32 v36, 16, v36
	v_cmp_gt_f32_e64 s[4:5], v34, v35
	s_nop 1
	v_cndmask_b32_e64 v189, v183, v36, s[4:5]
	v_sub_f32_e32 v176, v189, v182
	v_cmp_neq_f32_e32 vcc, 0, v176
	s_cbranch_vccz .LBB0_3617
	s_branch .Lil1_cont
;     ...
;         auto qk = [&](f32x16 (&s)[2], float& mi, int stg) {
;             const unsigned char* kb_ = lds + stg * STG + koff;
;             const unsigned mb = pk_bf16((m > -1e29f) ? -m : 0.f, 0.f) & 0xffffu;
;             mi = -__uint_as_float(mb << 16);
;             u32x4 qxw; qxw.x = hh ? 0u : mb; qxw.y = 0u; qxw.z = 0u; qxw.w = 0u;
;             u32x4 kxw; kxw.x = hh ? 0u : 0x3f80u; kxw.y = 0u; kxw.z = 0u; kxw.w = 0u;
;             const bf16x8 qx = __builtin_bit_cast(bf16x8, qxw), kx = __builtin_bit_cast(bf16x8, kxw);
;             f32x16 zero;
; #pragma unroll
;             for (int i = 0; i < 16; ++i) zero[i] = 0.f;
; #pragma unroll
;             for (int blk = 0; blk < 2; ++blk) {
;                 s[blk] = MFMA32(kx, qx, zero);
; #pragma unroll
;                 for (int ks = 0; ks < 4; ++ks) {
;                     const bf16x8 kf = *(const bf16x8*)(kb_ + blk * 4608 + ks * 32);
;                     s[blk] = MFMA32(kf, qf[ks], s[blk]);
;                 }
;             }
;         };
;     ...
;             if (MODE == 2) {
;                 const u64 wsh = wcur >> (4 * hh);
;                 const int wlo = (int)(unsigned)wsh, whi = (int)(unsigned)(wsh >> 32);
; #pragma unroll
;                 for (int i = 0; i < 16; ++i) {
;                     const int bit = (i & 3) + 8 * (i >> 2);
;                     const unsigned m0 = (unsigned)__builtin_amdgcn_sbfe(wlo, bit, 1), m1 = (unsigned)__builtin_amdgcn_sbfe(whi, bit, 1);
;                     s[0][i] = __uint_as_float((__float_as_uint(s[0][i]) & m0) | (0xff800000u & ~m0));
;                     s[1][i] = __uint_as_float((__float_as_uint(s[1][i]) & m1) | (0xff800000u & ~m1));
;                 }
;             } else if (k0 + 63 > qw0) {
; #pragma unroll
;                 for (int blk = 0; blk < 2; ++blk)
; #pragma unroll
;                     for (int i = 0; i < 16; ++i) { const int key = k0 + 32 * blk + crow(i, hh); if (key > myq) s[blk][i] = -INFINITY; }
;             }
;             float mx = s[0][0];
; #pragma unroll
;             for (int i = 1; i < 16; ++i) mx = fmaxf(mx, s[0][i]);
; #pragma unroll
;             for (int i = 0; i < 16; ++i) mx = fmaxf(mx, s[1][i]);
;             mx = xhalf_max(mx);
;             const float mabs = mi + mx;
;             const bool up = mabs > m + 8.0f;
;             const float mn = up ? __uint_as_float(pk_bf16(mabs, 0.f) << 16) : m;
.Lil2_fast:
	s_mov_b64 s[24:25], exec
	s_add_i32 s0, s44, 64
	v_cmp_lt_f32_e64 s[6:7], s31, v183
	s_mov_b64 vcc, s[2:3]
	v_mov_b32_e32 v245, v3
	v_mov_b32_e32 v246, v3
	v_cndmask_b32_e64 v244, 0, -v183, s[6:7]
	v_cvt_pk_bf16_f32 v248, v244, 0
	v_cndmask_b32_sdwa v244, v3, v248, vcc dst_sel:DWORD dst_unused:UNUSED_PAD src0_sel:DWORD src1_sel:WORD_0
	v_mov_b32_e32 v247, v3
	v_lshlrev_b32_e32 v249, 16, v248
	v_xor_b32_e32 v182, 0x80000000, v249
	v_mfma_f32_32x32x16_bf16 v[34:49], v[130:133], v[244:247], 0
	v_lshrrev_b64 v[6:7], v170, v[192:193]
	v_bfe_i32 v10, v6, 3, 1
	v_bfe_i32 v1, v6, 0, 1
	v_bitop3_b32 v17, v53, s34, v10 bitop3:0xe4
	v_bfe_i32 v10, v6, 8, 1
	v_bitop3_b32 v2, v50, s34, v1 bitop3:0xe4
	v_bfe_i32 v1, v6, 1, 1
	v_bitop3_b32 v16, v54, s34, v10 bitop3:0xe4
	v_bfe_i32 v10, v6, 9, 1
	v_bfe_i32 v8, v7, 1, 1
	v_bitop3_b32 v1, v51, s34, v1 bitop3:0xe4
	s_waitcnt lgkmcnt(7)
	v_mfma_f32_32x32x16_bf16 v[18:33], v[212:215], v[142:145], v[34:49]
	v_bfe_i32 v9, v7, 2, 1
	v_bitop3_b32 v55, v55, s34, v10 bitop3:0xe4
	v_bfe_i32 v10, v6, 10, 1
	v_bfe_i32 v50, v7, 16, 1
	v_bfe_i32 v51, v7, 17, 1
	v_bfe_i32 v4, v6, 2, 1
	v_bitop3_b32 v56, v56, s34, v10 bitop3:0xe4
	v_bfe_i32 v10, v6, 11, 1
	v_bitop3_b32 v67, v67, s34, v8 bitop3:0xe4
	v_bitop3_b32 v68, v68, s34, v9 bitop3:0xe4
	v_bitop3_b32 v8, v74, s34, v50 bitop3:0xe4
	s_waitcnt lgkmcnt(6)
	v_mfma_f32_32x32x16_bf16 v[18:33], v[216:219], v[146:149], v[18:33]
	v_bitop3_b32 v9, v75, s34, v51 bitop3:0xe4
	v_bitop3_b32 v4, v52, s34, v4 bitop3:0xe4
	v_bitop3_b32 v57, v57, s34, v10 bitop3:0xe4
	v_bfe_i32 v10, v6, 16, 1
	v_max_f32_e32 v50, v2, v1
	v_bitop3_b32 v58, v58, s34, v10 bitop3:0xe4
	v_bfe_i32 v10, v6, 17, 1
	v_max3_f32 v50, v50, v4, v17
	s_waitcnt lgkmcnt(5)
	v_mfma_f32_32x32x16_bf16 v[18:33], v[220:223], v[150:153], v[18:33]
	v_bitop3_b32 v59, v59, s34, v10 bitop3:0xe4
	v_bfe_i32 v10, v6, 18, 1
	v_max3_f32 v50, v50, v16, v55
	v_bitop3_b32 v60, v60, s34, v10 bitop3:0xe4
	v_bfe_i32 v10, v6, 19, 1
	v_max3_f32 v50, v50, v56, v57
	v_bfe_i32 v54, v6, 24, 1
	v_bfe_i32 v117, v6, 25, 1
	v_bitop3_b32 v61, v61, s34, v10 bitop3:0xe4
	v_max3_f32 v50, v50, v58, v59
	v_bfe_i32 v119, v6, 26, 1
	s_waitcnt lgkmcnt(4)
	v_mfma_f32_32x32x16_bf16 v[18:33], v[224:227], v[154:157], v[18:33]
	v_bfe_i32 v6, v6, 27, 1
	v_bitop3_b32 v62, v62, s34, v54 bitop3:0xe4
	v_bitop3_b32 v63, v63, s34, v117 bitop3:0xe4
	v_max3_f32 v50, v50, v60, v61
	v_bfe_i32 v5, v7, 0, 1
	v_bitop3_b32 v64, v64, s34, v119 bitop3:0xe4
	v_bitop3_b32 v65, v65, s34, v6 bitop3:0xe4
	v_max3_f32 v50, v50, v62, v63
	v_bfe_i32 v11, v7, 3, 1
	v_bitop3_b32 v66, v66, s34, v5 bitop3:0xe4
	v_max3_f32 v50, v50, v64, v65
	s_waitcnt lgkmcnt(3)
	v_mfma_f32_32x32x16_bf16 v[34:49], v[228:231], v[142:145], v[34:49]
	v_bfe_i32 v12, v7, 8, 1
	v_bfe_i32 v13, v7, 9, 1
	v_bitop3_b32 v69, v69, s34, v11 bitop3:0xe4
	v_max3_f32 v50, v50, v66, v67
	v_bfe_i32 v14, v7, 10, 1
	v_bfe_i32 v15, v7, 11, 1
	v_bitop3_b32 v70, v70, s34, v12 bitop3:0xe4
	v_bitop3_b32 v5, v71, s34, v13 bitop3:0xe4
	v_max3_f32 v50, v50, v68, v69
	v_bfe_i32 v52, v7, 18, 1
	v_bfe_i32 v53, v7, 19, 1
	s_waitcnt lgkmcnt(2)
	v_mfma_f32_32x32x16_bf16 v[34:49], v[232:235], v[146:149], v[34:49]
	v_bfe_i32 v116, v7, 24, 1
	v_bfe_i32 v118, v7, 25, 1
	v_bfe_i32 v120, v7, 26, 1
	v_bfe_i32 v121, v7, 27, 1
	v_bitop3_b32 v6, v72, s34, v14 bitop3:0xe4
	v_bitop3_b32 v7, v73, s34, v15 bitop3:0xe4
	v_max3_f32 v50, v50, v70, v5
	v_max3_f32 v50, v50, v6, v7
	v_bitop3_b32 v10, v76, s34, v52 bitop3:0xe4
	v_bitop3_b32 v11, v77, s34, v53 bitop3:0xe4
	s_waitcnt lgkmcnt(1)
	v_mfma_f32_32x32x16_bf16 v[34:49], v[236:239], v[150:153], v[34:49]
	v_max3_f32 v50, v50, v8, v9
	v_bitop3_b32 v12, v78, s34, v116 bitop3:0xe4
	v_bitop3_b32 v13, v79, s34, v118 bitop3:0xe4
	v_max3_f32 v50, v50, v10, v11
	v_bitop3_b32 v14, v80, s34, v120 bitop3:0xe4
	v_bitop3_b32 v15, v81, s34, v121 bitop3:0xe4
	v_max3_f32 v50, v50, v12, v13
	v_max3_f32 v50, v50, v14, v15
	v_mov_b32_e32 v51, v50
	s_nop 1
	v_permlane32_swap_b32_e32 v50, v51
	s_waitcnt lgkmcnt(0)
	v_mfma_f32_32x32x16_bf16 v[34:49], v[240:243], v[154:157], v[34:49]
	v_max_f32_e32 v176, v50, v51
	v_mov_b32_e32 v189, v183
	v_pk_add_f32 v[50:51], v[188:189], v[176:177]
	s_nop 0
	v_cvt_pk_bf16_f32 v52, v50, 0
	v_lshlrev_b32_e32 v52, 16, v52
	v_cmp_gt_f32_e64 s[6:7], v50, v51
	s_nop 1
	v_cndmask_b32_e64 v50, v183, v52, s[6:7]
	v_sub_f32_e32 v51, v50, v188
	v_cmp_neq_f32_e32 vcc, 0, v51
	s_cbranch_vccz .LBB0_3635
	s_branch .Lil2_cont
